# K1 BIAS1 loop: 40 loads per drain instead of 10; P6 GLU epilogue: gate loads of all 8 row groups issued up front
# baseline (speedup 1.0000x reference)
.LBB0_72:
	v_lshl_add_u64 v[116:117], v[12:13], 0, s[12:13]
	v_lshl_add_u64 v[118:119], v[14:15], 0, s[6:7]
	v_lshl_add_u64 v[118:119], v[118:119], 0, s[6:7]
	global_load_dwordx4 v[18:21], v[116:117], off offset:16
	global_load_dwordx4 v[22:25], v[116:117], off
	global_load_dword v26, v[14:15], off offset:-1024
	global_load_dword v27, v[14:15], off offset:-768
	global_load_dword v28, v[14:15], off offset:-512
	global_load_dword v29, v[14:15], off offset:-256
	global_load_dword v30, v[14:15], off
	global_load_dword v31, v[14:15], off offset:256
	global_load_dword v32, v[14:15], off offset:512
	global_load_dword v33, v[14:15], off offset:768
	global_load_dwordx4 v[84:87], v[116:117], off offset:48
	global_load_dwordx4 v[80:83], v[116:117], off offset:32
	global_load_dword v88, v[14:15], off offset:1024
	global_load_dword v89, v[14:15], off offset:1280
	global_load_dword v90, v[14:15], off offset:1536
	global_load_dword v91, v[14:15], off offset:1792
	global_load_dword v92, v[14:15], off offset:2048
	global_load_dword v93, v[14:15], off offset:2304
	global_load_dword v94, v[14:15], off offset:2560
	global_load_dword v95, v[14:15], off offset:2816
	global_load_dwordx4 v[100:103], v[116:117], off offset:80
	global_load_dwordx4 v[96:99], v[116:117], off offset:64
	global_load_dword v104, v[118:119], off offset:-1024
	global_load_dword v105, v[118:119], off offset:-768
	global_load_dword v106, v[118:119], off offset:-512
	global_load_dword v107, v[118:119], off offset:-256
	global_load_dword v108, v[118:119], off
	global_load_dword v109, v[118:119], off offset:256
	global_load_dword v110, v[118:119], off offset:512
	global_load_dword v111, v[118:119], off offset:768
	global_load_dwordx4 v[132:135], v[116:117], off offset:112
	global_load_dwordx4 v[128:131], v[116:117], off offset:96
	global_load_dword v136, v[118:119], off offset:1024
	global_load_dword v137, v[118:119], off offset:1280
	global_load_dword v138, v[118:119], off offset:1536
	global_load_dword v139, v[118:119], off offset:1792
	global_load_dword v140, v[118:119], off offset:2048
	global_load_dword v141, v[118:119], off offset:2304
	global_load_dword v142, v[118:119], off offset:2560
	global_load_dword v143, v[118:119], off offset:2816
	s_add_u32 s12, s12, 0x80
	s_addc_u32 s13, s13, 0
	v_lshl_add_u64 v[14:15], v[14:15], 0, s[6:7]
	v_lshl_add_u64 v[14:15], v[14:15], 0, s[6:7]
	v_lshl_add_u64 v[14:15], v[14:15], 0, s[6:7]
	v_lshl_add_u64 v[14:15], v[14:15], 0, s[6:7]
	s_cmpk_eq_i32 s12, 0x200
	s_waitcnt vmcnt(0)
	v_fmac_f32_e32 v17, v22, v26
	v_fmac_f32_e32 v17, v23, v27
	v_fmac_f32_e32 v17, v24, v28
	v_fmac_f32_e32 v17, v25, v29
	v_fmac_f32_e32 v17, v18, v30
	v_fmac_f32_e32 v17, v19, v31
	v_fmac_f32_e32 v17, v20, v32
	v_fmac_f32_e32 v17, v21, v33
	v_fmac_f32_e32 v17, v80, v88
	v_fmac_f32_e32 v17, v81, v89
	v_fmac_f32_e32 v17, v82, v90
	v_fmac_f32_e32 v17, v83, v91
	v_fmac_f32_e32 v17, v84, v92
	v_fmac_f32_e32 v17, v85, v93
	v_fmac_f32_e32 v17, v86, v94
	v_fmac_f32_e32 v17, v87, v95
	v_fmac_f32_e32 v17, v96, v104
	v_fmac_f32_e32 v17, v97, v105
	v_fmac_f32_e32 v17, v98, v106
	v_fmac_f32_e32 v17, v99, v107
	v_fmac_f32_e32 v17, v100, v108
	v_fmac_f32_e32 v17, v101, v109
	v_fmac_f32_e32 v17, v102, v110
	v_fmac_f32_e32 v17, v103, v111
	v_fmac_f32_e32 v17, v128, v136
	v_fmac_f32_e32 v17, v129, v137
	v_fmac_f32_e32 v17, v130, v138
	v_fmac_f32_e32 v17, v131, v139
	v_fmac_f32_e32 v17, v132, v140
	v_fmac_f32_e32 v17, v133, v141
	v_fmac_f32_e32 v17, v134, v142
	v_fmac_f32_e32 v17, v135, v143
	s_cbranch_scc0 .LBB0_72
	v_and_b32_e32 v12, 15, v16
	v_lshlrev_b32_e32 v7, 10, v7
	v_lshlrev_b32_e32 v12, 6, v12
	v_or3_b32 v12, v12, v7, v1
	v_readlane_b32 s12, v250, 13
	v_lshl_add_u64 v[10:11], v[10:11], 0, s[96:97]
	v_ashrrev_i32_e32 v13, 31, v12
	v_readlane_b32 s13, v250, 14
	v_cmp_lt_i64_e32 vcc, s[10:11], v[10:11]
	s_or_b64 s[4:5], vcc, s[4:5]
	v_lshl_add_u64 v[12:13], v[12:13], 2, s[12:13]
	global_store_dword v[12:13], v17, off
	s_andn2_b64 exec, exec, s[4:5]
	s_cbranch_execnz .LBB0_71

.LBB0_770:
	v_lshl_or_b32 v136, s25, 7, v146
	v_readlane_b32 s4, v254, 42
	v_ashrrev_i32_e32 v137, 31, v136
	v_readlane_b32 s5, v254, 43
	v_lshl_add_u32 v148, s13, 8, v144
	v_mov_b64_e32 v[140:141], s[84:85]
	v_lshl_add_u64 v[138:139], v[136:137], 2, s[4:5]
	global_load_dwordx4 v[150:153], v[138:139], off offset:1024
	global_load_dwordx4 v[154:157], v[138:139], off
	global_load_dwordx4 v[158:161], v[138:139], off offset:1040
	global_load_dwordx4 v[162:165], v[138:139], off offset:16
	v_mad_i64_i32 v[142:143], s[4:5], v148, s76, v[140:141]
	v_lshlrev_b64 v[136:137], 1, v[136:137]
	v_lshl_add_u64 v[166:167], v[142:143], 0, v[136:137]
	v_add_co_u32_e32 v166, vcc, 0x7e01000, v166
	v_mad_i64_i32 v[170:171], s[4:5], v148, s29, v[142:143]
	s_nop 0
	v_addc_co_u32_e32 v167, vcc, 0, v167, vcc
	s_mov_b32 s99, 0
	s_mov_b32 s98, 0x1e000
	v_lshl_add_u64 v[174:175], v[166:167], 0, s[98:99]
	global_load_dwordx4 v[176:179], v[174:175], off offset:3072
	s_mov_b32 s98, 0x3c000
	v_lshl_add_u64 v[174:175], v[166:167], 0, s[98:99]
	global_load_dwordx4 v[180:183], v[174:175], off offset:3072
	s_mov_b32 s98, 0x5a000
	v_lshl_add_u64 v[174:175], v[166:167], 0, s[98:99]
	global_load_dwordx4 v[184:187], v[174:175], off offset:3072
	s_mov_b32 s98, 0xf0000
	v_lshl_add_u64 v[174:175], v[166:167], 0, s[98:99]
	global_load_dwordx4 v[188:191], v[174:175], off offset:3072
	s_mov_b32 s98, 0x10e000
	v_lshl_add_u64 v[174:175], v[166:167], 0, s[98:99]
	global_load_dwordx4 v[192:195], v[174:175], off offset:3072
	s_mov_b32 s98, 0x12c000
	v_lshl_add_u64 v[174:175], v[166:167], 0, s[98:99]
	global_load_dwordx4 v[196:199], v[174:175], off offset:3072
	s_mov_b32 s98, 0x14a000
	v_lshl_add_u64 v[174:175], v[166:167], 0, s[98:99]
	global_load_dwordx4 v[200:203], v[174:175], off offset:3072
	global_load_dwordx4 v[166:169], v[166:167], off offset:3072
	v_lshl_add_u64 v[170:171], v[170:171], 0, v[136:137]
	v_or_b32_e32 v149, 16, v148
	v_add_co_u32_e32 v170, vcc, s2, v170
	v_mad_i64_i32 v[142:143], s[4:5], v149, s76, v[140:141]
	s_nop 0
	v_addc_co_u32_e32 v171, vcc, 0, v171, vcc
	v_lshl_add_u64 v[172:173], v[142:143], 0, v[136:137]
	s_mov_b32 s3, 0x7e01000
	v_readlane_b32 s96, v254, 29
	v_readlane_b32 s97, v254, 30
	v_readlane_b32 s87, v254, 27
	s_movk_i32 s33, 0x900
	s_waitcnt vmcnt(0)
	v_add_f32_e32 v150, v118, v150
	v_add_f32_e32 v151, v119, v151
	v_pk_add_f32 v[118:119], v[126:127], v[154:155]
	v_add_f32_e32 v126, v120, v152
	v_add_f32_e32 v127, v121, v153
	v_pk_add_f32 v[120:121], v[128:129], v[156:157]
	v_add_f32_e32 v128, v114, v158
	v_add_f32_e32 v129, v115, v159
	v_pk_add_f32 v[114:115], v[122:123], v[162:163]
	v_add_f32_e32 v122, v116, v160
	v_add_f32_e32 v123, v117, v161
	v_pk_add_f32 v[116:117], v[124:125], v[164:165]
	v_mul_f32_e32 v124, 0xbfb8aa3b, v150
	v_mul_f32_e32 v125, 0xbfb8aa3b, v151
	v_mul_f32_e32 v126, 0xbfb8aa3b, v126
	v_mul_f32_e32 v127, 0xbfb8aa3b, v127
	v_mul_f32_e32 v128, 0xbfb8aa3b, v128
	v_mul_f32_e32 v129, 0xbfb8aa3b, v129
	v_mul_f32_e32 v122, 0xbfb8aa3b, v122
	v_mul_f32_e32 v123, 0xbfb8aa3b, v123
	v_exp_f32_e32 v150, v124
	v_exp_f32_e32 v151, v125
	v_exp_f32_e32 v152, v126
	v_exp_f32_e32 v153, v127
	v_exp_f32_e32 v154, v128
	v_exp_f32_e32 v155, v129
	v_exp_f32_e32 v156, v122
	v_exp_f32_e32 v157, v123
	v_add_f32_e32 v150, 1.0, v150
	v_add_f32_e32 v151, 1.0, v151
	v_add_f32_e32 v152, 1.0, v152
	v_add_f32_e32 v153, 1.0, v153
	v_add_f32_e32 v154, 1.0, v154
	v_add_f32_e32 v155, 1.0, v155
	v_add_f32_e32 v156, 1.0, v156
	v_add_f32_e32 v157, 1.0, v157
	v_rcp_f32_e32 v150, v150
	v_rcp_f32_e32 v151, v151
	v_rcp_f32_e32 v152, v152
	v_rcp_f32_e32 v153, v153
	v_rcp_f32_e32 v154, v154
	v_rcp_f32_e32 v155, v155
	v_rcp_f32_e32 v156, v156
	v_rcp_f32_e32 v157, v157
	v_lshlrev_b32_e32 v122, 16, v166
	v_and_b32_e32 v123, 0xffff0000, v166
	v_lshlrev_b32_e32 v124, 16, v167
	v_and_b32_e32 v125, 0xffff0000, v167
	v_lshlrev_b32_e32 v126, 16, v168
	v_and_b32_e32 v127, 0xffff0000, v168
	v_lshlrev_b32_e32 v128, 16, v169
	v_and_b32_e32 v129, 0xffff0000, v169
	v_pk_mul_f32 v[118:119], v[118:119], v[150:151]
	v_pk_mul_f32 v[120:121], v[120:121], v[152:153]
	v_pk_mul_f32 v[114:115], v[114:115], v[154:155]
	v_pk_mul_f32 v[116:117], v[116:117], v[156:157]
	v_pk_mul_f32 v[118:119], v[118:119], v[122:123]
	v_pk_mul_f32 v[120:121], v[120:121], v[124:125]
	v_pk_mul_f32 v[122:123], v[114:115], v[126:127]
	v_pk_mul_f32 v[124:125], v[116:117], v[128:129]
	v_cvt_pk_bf16_f32 v114, v118, v119
	v_cvt_pk_bf16_f32 v115, v120, v121
	v_cvt_pk_bf16_f32 v116, v122, v123
	v_cvt_pk_bf16_f32 v117, v124, v125
	global_store_dwordx4 v[170:171], v[114:117], off offset:1536
	v_add_co_u32_e32 v118, vcc, s3, v172
	global_load_dwordx4 v[114:117], v[138:139], off offset:1024
	s_nop 0
	v_addc_co_u32_e32 v119, vcc, 0, v173, vcc
	s_nop 0
	global_load_dwordx4 v[124:127], v[138:139], off
	global_load_dwordx4 v[150:153], v[138:139], off offset:1040
	global_load_dwordx4 v[154:157], v[138:139], off offset:16
	v_mad_i64_i32 v[128:129], s[4:5], v149, s29, v[142:143]
	v_lshl_add_u64 v[128:129], v[128:129], 0, v[136:137]
	v_or_b32_e32 v158, 32, v148
	v_add_co_u32_e32 v128, vcc, s2, v128
	v_mad_i64_i32 v[118:119], s[4:5], v158, s76, v[140:141]
	s_nop 0
	v_addc_co_u32_e32 v129, vcc, 0, v129, vcc
	v_lshl_add_u64 v[142:143], v[118:119], 0, v[136:137]
	s_waitcnt vmcnt(3)
	v_add_f32_e32 v114, v102, v114
	v_add_f32_e32 v115, v103, v115
	s_waitcnt vmcnt(3)
	v_lshlrev_b32_e32 v102, 16, v176
	v_and_b32_e32 v103, 0xffff0000, v176
	s_waitcnt vmcnt(2)
	v_pk_add_f32 v[110:111], v[110:111], v[124:125]
	v_add_f32_e32 v116, v104, v116
	v_add_f32_e32 v117, v105, v117
	v_lshlrev_b32_e32 v104, 16, v177
	v_and_b32_e32 v105, 0xffff0000, v177
	s_waitcnt vmcnt(1)
	v_add_f32_e32 v120, v98, v150
	v_add_f32_e32 v121, v99, v151
	v_lshlrev_b32_e32 v98, 16, v178
	v_and_b32_e32 v99, 0xffff0000, v178
	v_add_f32_e32 v122, v100, v152
	v_add_f32_e32 v124, v101, v153
	v_lshlrev_b32_e32 v100, 16, v179
	v_and_b32_e32 v101, 0xffff0000, v179
	v_mul_f32_e32 v114, 0xbfb8aa3b, v114
	v_mul_f32_e32 v115, 0xbfb8aa3b, v115
	v_mul_f32_e32 v116, 0xbfb8aa3b, v116
	v_mul_f32_e32 v117, 0xbfb8aa3b, v117
	v_mul_f32_e32 v120, 0xbfb8aa3b, v120
	v_mul_f32_e32 v121, 0xbfb8aa3b, v121
	v_mul_f32_e32 v122, 0xbfb8aa3b, v122
	v_mul_f32_e32 v123, 0xbfb8aa3b, v124
	v_exp_f32_e32 v114, v114
	v_exp_f32_e32 v115, v115
	v_exp_f32_e32 v116, v116
	v_exp_f32_e32 v117, v117
	v_exp_f32_e32 v120, v120
	v_exp_f32_e32 v121, v121
	v_exp_f32_e32 v122, v122
	v_exp_f32_e32 v123, v123
	v_add_f32_e32 v114, 1.0, v114
	v_add_f32_e32 v115, 1.0, v115
	v_add_f32_e32 v116, 1.0, v116
	v_add_f32_e32 v117, 1.0, v117
	v_add_f32_e32 v120, 1.0, v120
	v_add_f32_e32 v121, 1.0, v121
	v_add_f32_e32 v122, 1.0, v122
	v_add_f32_e32 v123, 1.0, v123
	v_rcp_f32_e32 v114, v114
	v_rcp_f32_e32 v115, v115
	v_rcp_f32_e32 v116, v116
	v_rcp_f32_e32 v117, v117
	v_rcp_f32_e32 v120, v120
	v_rcp_f32_e32 v121, v121
	v_rcp_f32_e32 v122, v122
	v_rcp_f32_e32 v123, v123
	v_pk_add_f32 v[112:113], v[112:113], v[126:127]
	s_waitcnt vmcnt(0)
	v_pk_add_f32 v[106:107], v[106:107], v[154:155]
	v_pk_add_f32 v[108:109], v[108:109], v[156:157]
	v_pk_mul_f32 v[110:111], v[110:111], v[114:115]
	v_pk_mul_f32 v[112:113], v[112:113], v[116:117]
	v_pk_mul_f32 v[106:107], v[106:107], v[120:121]
	v_pk_mul_f32 v[108:109], v[108:109], v[122:123]
	v_pk_mul_f32 v[102:103], v[110:111], v[102:103]
	v_pk_mul_f32 v[104:105], v[112:113], v[104:105]
	v_pk_mul_f32 v[106:107], v[106:107], v[98:99]
	v_pk_mul_f32 v[108:109], v[108:109], v[100:101]
	v_cvt_pk_bf16_f32 v98, v102, v103
	v_cvt_pk_bf16_f32 v99, v104, v105
	v_cvt_pk_bf16_f32 v100, v106, v107
	v_cvt_pk_bf16_f32 v101, v108, v109
	global_store_dwordx4 v[128:129], v[98:101], off offset:1536
	v_add_co_u32_e32 v102, vcc, s3, v142
	global_load_dwordx4 v[98:101], v[138:139], off offset:1024
	s_nop 0
	v_addc_co_u32_e32 v103, vcc, 0, v143, vcc
	s_nop 0
	global_load_dwordx4 v[108:111], v[138:139], off
	global_load_dwordx4 v[112:115], v[138:139], off offset:1040
	global_load_dwordx4 v[120:123], v[138:139], off offset:16
	v_mad_i64_i32 v[116:117], s[4:5], v158, s29, v[118:119]
	v_lshl_add_u64 v[116:117], v[116:117], 0, v[136:137]
	v_or_b32_e32 v124, 48, v148
	v_add_co_u32_e32 v116, vcc, s2, v116
	v_mad_i64_i32 v[102:103], s[4:5], v124, s76, v[140:141]
	s_nop 0
	v_addc_co_u32_e32 v117, vcc, 0, v117, vcc
	v_lshl_add_u64 v[118:119], v[102:103], 0, v[136:137]
	s_waitcnt vmcnt(3)
	v_add_f32_e32 v98, v86, v98
	v_add_f32_e32 v99, v87, v99
	s_waitcnt vmcnt(3)
	v_lshlrev_b32_e32 v86, 16, v180
	v_and_b32_e32 v87, 0xffff0000, v180
	s_waitcnt vmcnt(2)
	v_pk_add_f32 v[94:95], v[94:95], v[108:109]
	v_add_f32_e32 v100, v88, v100
	v_add_f32_e32 v101, v89, v101
	v_lshlrev_b32_e32 v88, 16, v181
	v_and_b32_e32 v89, 0xffff0000, v181
	s_waitcnt vmcnt(1)
	v_add_f32_e32 v104, v82, v112
	v_add_f32_e32 v105, v83, v113
	v_lshlrev_b32_e32 v82, 16, v182
	v_and_b32_e32 v83, 0xffff0000, v182
	v_add_f32_e32 v106, v84, v114
	v_add_f32_e32 v108, v85, v115
	v_lshlrev_b32_e32 v84, 16, v183
	v_and_b32_e32 v85, 0xffff0000, v183
	v_mul_f32_e32 v98, 0xbfb8aa3b, v98
	v_mul_f32_e32 v99, 0xbfb8aa3b, v99
	v_mul_f32_e32 v100, 0xbfb8aa3b, v100
	v_mul_f32_e32 v101, 0xbfb8aa3b, v101
	v_mul_f32_e32 v104, 0xbfb8aa3b, v104
	v_mul_f32_e32 v105, 0xbfb8aa3b, v105
	v_mul_f32_e32 v106, 0xbfb8aa3b, v106
	v_mul_f32_e32 v107, 0xbfb8aa3b, v108
	v_exp_f32_e32 v98, v98
	v_exp_f32_e32 v99, v99
	v_exp_f32_e32 v100, v100
	v_exp_f32_e32 v101, v101
	v_exp_f32_e32 v104, v104
	v_exp_f32_e32 v105, v105
	v_exp_f32_e32 v106, v106
	v_exp_f32_e32 v107, v107
	v_add_f32_e32 v98, 1.0, v98
	v_add_f32_e32 v99, 1.0, v99
	v_add_f32_e32 v100, 1.0, v100
	v_add_f32_e32 v101, 1.0, v101
	v_add_f32_e32 v104, 1.0, v104
	v_add_f32_e32 v105, 1.0, v105
	v_add_f32_e32 v106, 1.0, v106
	v_add_f32_e32 v107, 1.0, v107
	v_rcp_f32_e32 v98, v98
	v_rcp_f32_e32 v99, v99
	v_rcp_f32_e32 v100, v100
	v_rcp_f32_e32 v101, v101
	v_rcp_f32_e32 v104, v104
	v_rcp_f32_e32 v105, v105
	v_rcp_f32_e32 v106, v106
	v_rcp_f32_e32 v107, v107
	v_pk_add_f32 v[96:97], v[96:97], v[110:111]
	s_waitcnt vmcnt(0)
	v_pk_add_f32 v[90:91], v[90:91], v[120:121]
	v_pk_add_f32 v[92:93], v[92:93], v[122:123]
	v_pk_mul_f32 v[94:95], v[94:95], v[98:99]
	v_pk_mul_f32 v[96:97], v[96:97], v[100:101]
	v_pk_mul_f32 v[90:91], v[90:91], v[104:105]
	v_pk_mul_f32 v[92:93], v[92:93], v[106:107]
	v_pk_mul_f32 v[86:87], v[94:95], v[86:87]
	v_pk_mul_f32 v[88:89], v[96:97], v[88:89]
	v_pk_mul_f32 v[90:91], v[90:91], v[82:83]
	v_pk_mul_f32 v[92:93], v[92:93], v[84:85]
	v_cvt_pk_bf16_f32 v82, v86, v87
	v_cvt_pk_bf16_f32 v83, v88, v89
	v_cvt_pk_bf16_f32 v84, v90, v91
	v_cvt_pk_bf16_f32 v85, v92, v93
	global_store_dwordx4 v[116:117], v[82:85], off offset:1536
	v_add_co_u32_e32 v86, vcc, s3, v118
	global_load_dwordx4 v[82:85], v[138:139], off offset:1024
	s_nop 0
	v_addc_co_u32_e32 v87, vcc, 0, v119, vcc
	s_nop 0
	global_load_dwordx4 v[92:95], v[138:139], off
	global_load_dwordx4 v[96:99], v[138:139], off offset:1040
	global_load_dwordx4 v[104:107], v[138:139], off offset:16
	v_mad_i64_i32 v[100:101], s[4:5], v124, s29, v[102:103]
	v_lshl_add_u64 v[100:101], v[100:101], 0, v[136:137]
	v_add_u32_e32 v108, 0x80, v148
	v_add_co_u32_e32 v100, vcc, s2, v100
	v_mad_i64_i32 v[86:87], s[4:5], v108, s76, v[140:141]
	s_nop 0
	v_addc_co_u32_e32 v101, vcc, 0, v101, vcc
	v_lshl_add_u64 v[102:103], v[86:87], 0, v[136:137]
	s_waitcnt vmcnt(3)
	v_add_f32_e32 v82, v70, v82
	v_add_f32_e32 v83, v71, v83
	s_waitcnt vmcnt(3)
	v_lshlrev_b32_e32 v70, 16, v184
	v_and_b32_e32 v71, 0xffff0000, v184
	s_waitcnt vmcnt(2)
	v_pk_add_f32 v[78:79], v[78:79], v[92:93]
	v_add_f32_e32 v84, v72, v84
	v_add_f32_e32 v85, v73, v85
	v_lshlrev_b32_e32 v72, 16, v185
	v_and_b32_e32 v73, 0xffff0000, v185
	s_waitcnt vmcnt(1)
	v_add_f32_e32 v88, v66, v96
	v_add_f32_e32 v89, v67, v97
	v_lshlrev_b32_e32 v66, 16, v186
	v_and_b32_e32 v67, 0xffff0000, v186
	v_add_f32_e32 v90, v68, v98
	v_add_f32_e32 v92, v69, v99
	v_lshlrev_b32_e32 v68, 16, v187
	v_and_b32_e32 v69, 0xffff0000, v187
	v_mul_f32_e32 v82, 0xbfb8aa3b, v82
	v_mul_f32_e32 v83, 0xbfb8aa3b, v83
	v_mul_f32_e32 v84, 0xbfb8aa3b, v84
	v_mul_f32_e32 v85, 0xbfb8aa3b, v85
	v_mul_f32_e32 v88, 0xbfb8aa3b, v88
	v_mul_f32_e32 v89, 0xbfb8aa3b, v89
	v_mul_f32_e32 v90, 0xbfb8aa3b, v90
	v_mul_f32_e32 v91, 0xbfb8aa3b, v92
	v_exp_f32_e32 v82, v82
	v_exp_f32_e32 v83, v83
	v_exp_f32_e32 v84, v84
	v_exp_f32_e32 v85, v85
	v_exp_f32_e32 v88, v88
	v_exp_f32_e32 v89, v89
	v_exp_f32_e32 v90, v90
	v_exp_f32_e32 v91, v91
	v_add_f32_e32 v82, 1.0, v82
	v_add_f32_e32 v83, 1.0, v83
	v_add_f32_e32 v84, 1.0, v84
	v_add_f32_e32 v85, 1.0, v85
	v_add_f32_e32 v88, 1.0, v88
	v_add_f32_e32 v89, 1.0, v89
	v_add_f32_e32 v90, 1.0, v90
	v_add_f32_e32 v91, 1.0, v91
	v_rcp_f32_e32 v82, v82
	v_rcp_f32_e32 v83, v83
	v_rcp_f32_e32 v84, v84
	v_rcp_f32_e32 v85, v85
	v_rcp_f32_e32 v88, v88
	v_rcp_f32_e32 v89, v89
	v_rcp_f32_e32 v90, v90
	v_rcp_f32_e32 v91, v91
	v_pk_add_f32 v[80:81], v[80:81], v[94:95]
	s_waitcnt vmcnt(0)
	v_pk_add_f32 v[74:75], v[74:75], v[104:105]
	v_pk_add_f32 v[76:77], v[76:77], v[106:107]
	v_pk_mul_f32 v[78:79], v[78:79], v[82:83]
	v_pk_mul_f32 v[80:81], v[80:81], v[84:85]
	v_pk_mul_f32 v[74:75], v[74:75], v[88:89]
	v_pk_mul_f32 v[76:77], v[76:77], v[90:91]
	v_pk_mul_f32 v[70:71], v[78:79], v[70:71]
	v_pk_mul_f32 v[72:73], v[80:81], v[72:73]
	v_pk_mul_f32 v[74:75], v[74:75], v[66:67]
	v_pk_mul_f32 v[76:77], v[76:77], v[68:69]
	v_cvt_pk_bf16_f32 v66, v70, v71
	v_cvt_pk_bf16_f32 v67, v72, v73
	v_cvt_pk_bf16_f32 v68, v74, v75
	v_cvt_pk_bf16_f32 v69, v76, v77
	global_store_dwordx4 v[100:101], v[66:69], off offset:1536
	v_add_co_u32_e32 v70, vcc, s3, v102
	global_load_dwordx4 v[66:69], v[138:139], off offset:1024
	s_nop 0
	v_addc_co_u32_e32 v71, vcc, 0, v103, vcc
	s_nop 0
	global_load_dwordx4 v[76:79], v[138:139], off
	global_load_dwordx4 v[80:83], v[138:139], off offset:1040
	global_load_dwordx4 v[88:91], v[138:139], off offset:16
	v_mad_i64_i32 v[84:85], s[4:5], v108, s29, v[86:87]
	v_lshl_add_u64 v[84:85], v[84:85], 0, v[136:137]
	v_add_u32_e32 v92, 0x90, v148
	v_add_co_u32_e32 v84, vcc, s2, v84
	v_mad_i64_i32 v[70:71], s[4:5], v92, s76, v[140:141]
	s_nop 0
	v_addc_co_u32_e32 v85, vcc, 0, v85, vcc
	v_lshl_add_u64 v[86:87], v[70:71], 0, v[136:137]
	s_waitcnt vmcnt(3)
	v_add_f32_e32 v66, v52, v66
	v_add_f32_e32 v67, v53, v67
	s_waitcnt vmcnt(3)
	v_lshlrev_b32_e32 v52, 16, v188
	v_and_b32_e32 v53, 0xffff0000, v188
	s_waitcnt vmcnt(2)
	v_pk_add_f32 v[60:61], v[60:61], v[76:77]
	v_add_f32_e32 v68, v54, v68
	v_add_f32_e32 v69, v55, v69
	v_lshlrev_b32_e32 v54, 16, v189
	v_and_b32_e32 v55, 0xffff0000, v189
	s_waitcnt vmcnt(1)
	v_add_f32_e32 v72, v48, v80
	v_add_f32_e32 v73, v49, v81
	v_lshlrev_b32_e32 v48, 16, v190
	v_and_b32_e32 v49, 0xffff0000, v190
	v_add_f32_e32 v74, v50, v82
	v_add_f32_e32 v76, v51, v83
	v_lshlrev_b32_e32 v50, 16, v191
	v_and_b32_e32 v51, 0xffff0000, v191
	v_mul_f32_e32 v66, 0xbfb8aa3b, v66
	v_mul_f32_e32 v67, 0xbfb8aa3b, v67
	v_mul_f32_e32 v68, 0xbfb8aa3b, v68
	v_mul_f32_e32 v69, 0xbfb8aa3b, v69
	v_mul_f32_e32 v72, 0xbfb8aa3b, v72
	v_mul_f32_e32 v73, 0xbfb8aa3b, v73
	v_mul_f32_e32 v74, 0xbfb8aa3b, v74
	v_mul_f32_e32 v75, 0xbfb8aa3b, v76
	v_exp_f32_e32 v66, v66
	v_exp_f32_e32 v67, v67
	v_exp_f32_e32 v68, v68
	v_exp_f32_e32 v69, v69
	v_exp_f32_e32 v72, v72
	v_exp_f32_e32 v73, v73
	v_exp_f32_e32 v74, v74
	v_exp_f32_e32 v75, v75
	v_add_f32_e32 v66, 1.0, v66
	v_add_f32_e32 v67, 1.0, v67
	v_add_f32_e32 v68, 1.0, v68
	v_add_f32_e32 v69, 1.0, v69
	v_add_f32_e32 v72, 1.0, v72
	v_add_f32_e32 v73, 1.0, v73
	v_add_f32_e32 v74, 1.0, v74
	v_add_f32_e32 v75, 1.0, v75
	v_rcp_f32_e32 v66, v66
	v_rcp_f32_e32 v67, v67
	v_rcp_f32_e32 v68, v68
	v_rcp_f32_e32 v69, v69
	v_rcp_f32_e32 v72, v72
	v_rcp_f32_e32 v73, v73
	v_rcp_f32_e32 v74, v74
	v_rcp_f32_e32 v75, v75
	v_pk_add_f32 v[62:63], v[62:63], v[78:79]
	s_waitcnt vmcnt(0)
	v_pk_add_f32 v[56:57], v[56:57], v[88:89]
	v_pk_add_f32 v[58:59], v[58:59], v[90:91]
	v_pk_mul_f32 v[60:61], v[60:61], v[66:67]
	v_pk_mul_f32 v[62:63], v[62:63], v[68:69]
	v_pk_mul_f32 v[56:57], v[56:57], v[72:73]
	v_pk_mul_f32 v[58:59], v[58:59], v[74:75]
	v_pk_mul_f32 v[52:53], v[60:61], v[52:53]
	v_pk_mul_f32 v[54:55], v[62:63], v[54:55]
	v_pk_mul_f32 v[56:57], v[56:57], v[48:49]
	v_pk_mul_f32 v[58:59], v[58:59], v[50:51]
	v_cvt_pk_bf16_f32 v48, v52, v53
	v_cvt_pk_bf16_f32 v49, v54, v55
	v_cvt_pk_bf16_f32 v50, v56, v57
	v_cvt_pk_bf16_f32 v51, v58, v59
	global_store_dwordx4 v[84:85], v[48:51], off offset:1536
	v_add_co_u32_e32 v52, vcc, s3, v86
	global_load_dwordx4 v[48:51], v[138:139], off offset:1024
	s_nop 0
	v_addc_co_u32_e32 v53, vcc, 0, v87, vcc
	s_nop 0
	global_load_dwordx4 v[58:61], v[138:139], off
	global_load_dwordx4 v[66:69], v[138:139], off offset:1040
	global_load_dwordx4 v[72:75], v[138:139], off offset:16
	v_mad_i64_i32 v[62:63], s[4:5], v92, s29, v[70:71]
	v_lshl_add_u64 v[62:63], v[62:63], 0, v[136:137]
	v_add_u32_e32 v76, 0xa0, v148
	v_add_co_u32_e32 v62, vcc, s2, v62
	v_mad_i64_i32 v[52:53], s[4:5], v76, s76, v[140:141]
	s_nop 0
	v_addc_co_u32_e32 v63, vcc, 0, v63, vcc
	v_lshl_add_u64 v[70:71], v[52:53], 0, v[136:137]
	s_waitcnt vmcnt(3)
	v_add_f32_e32 v48, v36, v48
	v_add_f32_e32 v49, v37, v49
	s_waitcnt vmcnt(3)
	v_lshlrev_b32_e32 v36, 16, v192
	v_and_b32_e32 v37, 0xffff0000, v192
	s_waitcnt vmcnt(2)
	v_pk_add_f32 v[44:45], v[44:45], v[58:59]
	v_add_f32_e32 v50, v38, v50
	v_add_f32_e32 v51, v39, v51
	v_lshlrev_b32_e32 v38, 16, v193
	v_and_b32_e32 v39, 0xffff0000, v193
	s_waitcnt vmcnt(1)
	v_add_f32_e32 v54, v32, v66
	v_add_f32_e32 v55, v33, v67
	v_lshlrev_b32_e32 v32, 16, v194
	v_and_b32_e32 v33, 0xffff0000, v194
	v_add_f32_e32 v56, v34, v68
	v_add_f32_e32 v58, v35, v69
	v_lshlrev_b32_e32 v34, 16, v195
	v_and_b32_e32 v35, 0xffff0000, v195
	v_mul_f32_e32 v48, 0xbfb8aa3b, v48
	v_mul_f32_e32 v49, 0xbfb8aa3b, v49
	v_mul_f32_e32 v50, 0xbfb8aa3b, v50
	v_mul_f32_e32 v51, 0xbfb8aa3b, v51
	v_mul_f32_e32 v54, 0xbfb8aa3b, v54
	v_mul_f32_e32 v55, 0xbfb8aa3b, v55
	v_mul_f32_e32 v56, 0xbfb8aa3b, v56
	v_mul_f32_e32 v57, 0xbfb8aa3b, v58
	v_exp_f32_e32 v48, v48
	v_exp_f32_e32 v49, v49
	v_exp_f32_e32 v50, v50
	v_exp_f32_e32 v51, v51
	v_exp_f32_e32 v54, v54
	v_exp_f32_e32 v55, v55
	v_exp_f32_e32 v56, v56
	v_exp_f32_e32 v57, v57
	v_add_f32_e32 v48, 1.0, v48
	v_add_f32_e32 v49, 1.0, v49
	v_add_f32_e32 v50, 1.0, v50
	v_add_f32_e32 v51, 1.0, v51
	v_add_f32_e32 v54, 1.0, v54
	v_add_f32_e32 v55, 1.0, v55
	v_add_f32_e32 v56, 1.0, v56
	v_add_f32_e32 v57, 1.0, v57
	v_rcp_f32_e32 v48, v48
	v_rcp_f32_e32 v49, v49
	v_rcp_f32_e32 v50, v50
	v_rcp_f32_e32 v51, v51
	v_rcp_f32_e32 v54, v54
	v_rcp_f32_e32 v55, v55
	v_rcp_f32_e32 v56, v56
	v_rcp_f32_e32 v57, v57
	v_pk_add_f32 v[46:47], v[46:47], v[60:61]
	s_waitcnt vmcnt(0)
	v_pk_add_f32 v[40:41], v[40:41], v[72:73]
	v_pk_add_f32 v[42:43], v[42:43], v[74:75]
	v_pk_mul_f32 v[44:45], v[44:45], v[48:49]
	v_pk_mul_f32 v[46:47], v[46:47], v[50:51]
	v_pk_mul_f32 v[40:41], v[40:41], v[54:55]
	v_pk_mul_f32 v[42:43], v[42:43], v[56:57]
	v_pk_mul_f32 v[36:37], v[44:45], v[36:37]
	v_pk_mul_f32 v[38:39], v[46:47], v[38:39]
	v_pk_mul_f32 v[40:41], v[40:41], v[32:33]
	v_pk_mul_f32 v[42:43], v[42:43], v[34:35]
	v_cvt_pk_bf16_f32 v32, v36, v37
	v_cvt_pk_bf16_f32 v33, v38, v39
	v_cvt_pk_bf16_f32 v34, v40, v41
	v_cvt_pk_bf16_f32 v35, v42, v43
	global_store_dwordx4 v[62:63], v[32:35], off offset:1536
	v_add_co_u32_e32 v36, vcc, s3, v70
	global_load_dwordx4 v[32:35], v[138:139], off offset:1024
	s_nop 0
	v_addc_co_u32_e32 v37, vcc, 0, v71, vcc
	s_nop 0
	global_load_dwordx4 v[42:45], v[138:139], off
	global_load_dwordx4 v[46:49], v[138:139], off offset:1040
	global_load_dwordx4 v[54:57], v[138:139], off offset:16
	v_mad_i64_i32 v[50:51], s[4:5], v76, s29, v[52:53]
	v_lshl_add_u64 v[50:51], v[50:51], 0, v[136:137]
	v_add_u32_e32 v58, 0xb0, v148
	v_add_co_u32_e32 v50, vcc, s2, v50
	v_mad_i64_i32 v[36:37], s[4:5], v58, s76, v[140:141]
	s_nop 0
	v_addc_co_u32_e32 v51, vcc, 0, v51, vcc
	v_lshl_add_u64 v[52:53], v[36:37], 0, v[136:137]
	v_mad_i64_i32 v[36:37], s[4:5], v58, s29, v[36:37]
	v_lshl_add_u64 v[36:37], v[36:37], 0, v[136:137]
	s_mov_b64 s[4:5], -1
	s_waitcnt vmcnt(3)
	v_add_f32_e32 v32, v20, v32
	v_add_f32_e32 v33, v21, v33
	s_waitcnt vmcnt(3)
	v_lshlrev_b32_e32 v20, 16, v196
	v_and_b32_e32 v21, 0xffff0000, v196
	s_waitcnt vmcnt(2)
	v_pk_add_f32 v[28:29], v[28:29], v[42:43]
	v_add_f32_e32 v34, v22, v34
	v_add_f32_e32 v35, v23, v35
	v_lshlrev_b32_e32 v22, 16, v197
	v_and_b32_e32 v23, 0xffff0000, v197
	s_waitcnt vmcnt(1)
	v_add_f32_e32 v38, v16, v46
	v_add_f32_e32 v39, v17, v47
	v_lshlrev_b32_e32 v16, 16, v198
	v_and_b32_e32 v17, 0xffff0000, v198
	v_add_f32_e32 v40, v18, v48
	v_add_f32_e32 v42, v19, v49
	v_lshlrev_b32_e32 v18, 16, v199
	v_and_b32_e32 v19, 0xffff0000, v199
	v_mul_f32_e32 v32, 0xbfb8aa3b, v32
	v_mul_f32_e32 v33, 0xbfb8aa3b, v33
	v_mul_f32_e32 v34, 0xbfb8aa3b, v34
	v_mul_f32_e32 v35, 0xbfb8aa3b, v35
	v_mul_f32_e32 v38, 0xbfb8aa3b, v38
	v_mul_f32_e32 v39, 0xbfb8aa3b, v39
	v_mul_f32_e32 v40, 0xbfb8aa3b, v40
	v_mul_f32_e32 v41, 0xbfb8aa3b, v42
	v_exp_f32_e32 v32, v32
	v_exp_f32_e32 v33, v33
	v_exp_f32_e32 v34, v34
	v_exp_f32_e32 v35, v35
	v_exp_f32_e32 v38, v38
	v_exp_f32_e32 v39, v39
	v_exp_f32_e32 v40, v40
	v_exp_f32_e32 v41, v41
	v_add_f32_e32 v32, 1.0, v32
	v_add_f32_e32 v33, 1.0, v33
	v_add_f32_e32 v34, 1.0, v34
	v_add_f32_e32 v35, 1.0, v35
	v_add_f32_e32 v38, 1.0, v38
	v_add_f32_e32 v39, 1.0, v39
	v_add_f32_e32 v40, 1.0, v40
	v_add_f32_e32 v41, 1.0, v41
	v_rcp_f32_e32 v32, v32
	v_rcp_f32_e32 v33, v33
	v_rcp_f32_e32 v34, v34
	v_rcp_f32_e32 v35, v35
	v_rcp_f32_e32 v38, v38
	v_rcp_f32_e32 v39, v39
	v_rcp_f32_e32 v40, v40
	v_rcp_f32_e32 v41, v41
	v_pk_add_f32 v[30:31], v[30:31], v[44:45]
	s_waitcnt vmcnt(0)
	v_pk_add_f32 v[24:25], v[24:25], v[54:55]
	v_pk_add_f32 v[26:27], v[26:27], v[56:57]
	v_pk_mul_f32 v[28:29], v[28:29], v[32:33]
	v_pk_mul_f32 v[30:31], v[30:31], v[34:35]
	v_pk_mul_f32 v[24:25], v[24:25], v[38:39]
	v_pk_mul_f32 v[26:27], v[26:27], v[40:41]
	v_pk_mul_f32 v[20:21], v[28:29], v[20:21]
	v_pk_mul_f32 v[22:23], v[30:31], v[22:23]
	v_pk_mul_f32 v[24:25], v[24:25], v[16:17]
	v_pk_mul_f32 v[26:27], v[26:27], v[18:19]
	v_cvt_pk_bf16_f32 v16, v20, v21
	v_cvt_pk_bf16_f32 v17, v22, v23
	v_cvt_pk_bf16_f32 v18, v24, v25
	v_cvt_pk_bf16_f32 v19, v26, v27
	global_store_dwordx4 v[50:51], v[16:19], off offset:1536
	v_add_co_u32_e32 v20, vcc, s3, v52
	global_load_dwordx4 v[16:19], v[138:139], off offset:1024
	s_nop 0
	v_addc_co_u32_e32 v21, vcc, 0, v53, vcc
	s_nop 0
	s_nop 0
	global_load_dwordx4 v[24:27], v[138:139], off
	global_load_dwordx4 v[28:31], v[138:139], off offset:1040
	global_load_dwordx4 v[32:35], v[138:139], off offset:16
	v_add_co_u32_e32 v36, vcc, 0x1a800000, v36
	s_waitcnt vmcnt(3)
	v_add_f32_e32 v16, v4, v16
	v_add_f32_e32 v17, v5, v17
	s_waitcnt vmcnt(3)
	v_lshlrev_b32_e32 v4, 16, v200
	v_and_b32_e32 v5, 0xffff0000, v200
	s_waitcnt vmcnt(2)
	v_pk_add_f32 v[12:13], v[12:13], v[24:25]
	v_add_f32_e32 v18, v6, v18
	v_add_f32_e32 v19, v7, v19
	v_lshlrev_b32_e32 v6, 16, v201
	v_and_b32_e32 v7, 0xffff0000, v201
	s_waitcnt vmcnt(1)
	v_add_f32_e32 v20, v0, v28
	v_add_f32_e32 v21, v1, v29
	v_lshlrev_b32_e32 v0, 16, v202
	v_and_b32_e32 v1, 0xffff0000, v202
	v_add_f32_e32 v22, v2, v30
	v_add_f32_e32 v24, v3, v31
	v_lshlrev_b32_e32 v2, 16, v203
	v_and_b32_e32 v3, 0xffff0000, v203
	v_mul_f32_e32 v16, 0xbfb8aa3b, v16
	v_mul_f32_e32 v17, 0xbfb8aa3b, v17
	v_mul_f32_e32 v18, 0xbfb8aa3b, v18
	v_mul_f32_e32 v19, 0xbfb8aa3b, v19
	v_mul_f32_e32 v20, 0xbfb8aa3b, v20
	v_mul_f32_e32 v21, 0xbfb8aa3b, v21
	v_mul_f32_e32 v22, 0xbfb8aa3b, v22
	v_mul_f32_e32 v23, 0xbfb8aa3b, v24
	v_exp_f32_e32 v16, v16
	v_exp_f32_e32 v17, v17
	v_exp_f32_e32 v18, v18
	v_exp_f32_e32 v19, v19
	v_exp_f32_e32 v20, v20
	v_exp_f32_e32 v21, v21
	v_exp_f32_e32 v22, v22
	v_exp_f32_e32 v23, v23
	v_add_f32_e32 v16, 1.0, v16
	v_add_f32_e32 v17, 1.0, v17
	v_add_f32_e32 v18, 1.0, v18
	v_add_f32_e32 v19, 1.0, v19
	v_add_f32_e32 v20, 1.0, v20
	v_add_f32_e32 v21, 1.0, v21
	v_add_f32_e32 v22, 1.0, v22
	v_add_f32_e32 v23, 1.0, v23
	v_rcp_f32_e32 v16, v16
	v_rcp_f32_e32 v17, v17
	v_rcp_f32_e32 v18, v18
	v_rcp_f32_e32 v19, v19
	v_rcp_f32_e32 v20, v20
	v_rcp_f32_e32 v21, v21
	v_rcp_f32_e32 v22, v22
	v_rcp_f32_e32 v23, v23
	v_pk_add_f32 v[14:15], v[14:15], v[26:27]
	s_waitcnt vmcnt(0)
	v_pk_add_f32 v[8:9], v[8:9], v[32:33]
	v_pk_add_f32 v[10:11], v[10:11], v[34:35]
	v_pk_mul_f32 v[12:13], v[12:13], v[16:17]
	v_pk_mul_f32 v[14:15], v[14:15], v[18:19]
	v_pk_mul_f32 v[8:9], v[8:9], v[20:21]
	v_pk_mul_f32 v[10:11], v[10:11], v[22:23]
	v_pk_mul_f32 v[4:5], v[12:13], v[4:5]
	v_pk_mul_f32 v[6:7], v[14:15], v[6:7]
	v_pk_mul_f32 v[8:9], v[8:9], v[0:1]
	v_pk_mul_f32 v[10:11], v[10:11], v[2:3]
	v_addc_co_u32_e32 v37, vcc, 0, v37, vcc
	v_cvt_pk_bf16_f32 v0, v4, v5
	v_cvt_pk_bf16_f32 v1, v6, v7
	v_cvt_pk_bf16_f32 v2, v8, v9
	v_cvt_pk_bf16_f32 v3, v10, v11
	global_store_dwordx4 v[36:37], v[0:3], off offset:1536
	s_andn2_b64 vcc, exec, s[46:47]
	s_cbranch_vccnz .LBB0_763
	s_andn2_b64 vcc, exec, s[0:1]
	s_cbranch_vccnz .LBB0_762
	s_barrier
	s_branch .LBB0_762
